# attention: next-tile LDS staging (K write + V transpose pack) issued in the shadow of the last PV MFMA group
# speedup vs baseline: 1.0147x; 1.0016x over previous
; #define LAS __attribute__((address_space(3)))
; __device__ __forceinline__ unsigned cvtpk(float lo, float hi) { f32x2_t v = {lo, hi}; bf16x2_t b = __builtin_convertvector(v, bf16x2_t); return __builtin_bit_cast(unsigned, b); }
; __device__ __forceinline__ void unit(unsigned char* ws, LAS unsigned char* lds, int b, int h, int mp, int qb, const int tid_in) {
;     ...
;             for (int jt = 0; jt < 4; ++jt) {
; #pragma unroll
;                 for (int jj = 0; jj < 4; ++jj) s[g][jt][jj] = __builtin_amdgcn_exp2f(s[g][jt][jj]); }
; #pragma unroll
;             for (int sb = 0; sb < 2; ++sb) { u32x4 pw; pw.x = cvtpk(s[g][2 * sb][0], s[g][2 * sb][1]); pw.y = cvtpk(s[g][2 * sb][2], s[g][2 * sb][3]); pw.z = cvtpk(s[g][2 * sb + 1][0], s[g][2 * sb + 1][1]); pw.w = cvtpk(s[g][2 * sb + 1][2], s[g][2 * sb + 1][3]);
;                 pf[g][sb] = __builtin_bit_cast(bf16x8, pw); }
;         }
; #pragma unroll
;         for (int g = 0; g < 2; ++g) {
;             lacc[g] = __builtin_amdgcn_mfma_f32_16x16x32_bf16(onesf, pf[g][0], lacc[g], 0, 0, 0); lacc[g] = __builtin_amdgcn_mfma_f32_16x16x32_bf16(onesf, pf[g][1], lacc[g], 0, 0, 0); }
; #pragma unroll
;         for (int et = 0; et < 8; ++et) { const LAS bf16_t* vrow = VT + (16 * et + fr) * KP;
;             const bf16x8 vf0 = *(const LAS bf16x8*)(vrow + ((8 * fq + 8 * et) & 63)), vf1 = *(const LAS bf16x8*)(vrow + ((32 + 8 * fq + 8 * et) & 63));
; #pragma unroll
;             for (int g = 0; g < 2; ++g) { o[g][et] = __builtin_amdgcn_mfma_f32_16x16x32_bf16(vf0, pf[g][0], o[g][et], 0, 0, 0); o[g][et] = __builtin_amdgcn_mfma_f32_16x16x32_bf16(vf1, pf[g][1], o[g][et], 0, 0, 0); } }
;         }
;         if (kt + 1 < NT) { FA3_STAGE((kt + 1) & 1); kA = kB; vA0 = vB0; vA1 = vB1;
.LBB0_195:
	v_lshl_add_u32 v210, v168, 1, v179
	v_lshl_add_u32 v211, v167, 1, v179
	v_lshl_add_u32 v212, v166, 1, v179
	v_mov_b32_e32 v206, s20
	v_mov_b32_e32 v207, s20
	v_mov_b32_e32 v208, s20
	v_mov_b32_e32 v209, s20
	ds_read_b128 v[222:225], v178 offset:9216
	ds_read_b128 v[226:229], v178 offset:11536
	ds_read_b128 v[230:233], v178 offset:13856
	ds_read_b128 v[234:237], v178 offset:16176
	ds_read_b128 v[238:241], v178 offset:18496
	ds_read_b128 v[242:245], v210 offset:20736
	ds_read_b128 v[246:249], v211 offset:23040
	ds_read_b128 v[250:253], v212 offset:25344
	v_exp_f32_e32 v126, v126
	v_exp_f32_e32 v127, v127
	v_exp_f32_e32 v128, v128
	v_exp_f32_e32 v129, v129
	v_exp_f32_e32 v130, v130
	v_exp_f32_e32 v131, v131
	v_exp_f32_e32 v132, v132
	v_exp_f32_e32 v133, v133
	v_cvt_pk_bf16_f32 v126, v126, v127
	v_cvt_pk_bf16_f32 v127, v128, v129
	v_cvt_pk_bf16_f32 v128, v130, v131
	v_cvt_pk_bf16_f32 v129, v132, v133
	s_nop 1
	s_waitcnt lgkmcnt(7)
	v_mfma_f32_16x16x32_bf16 v[70:73], v[206:209], v[126:129], v[70:73]
	v_exp_f32_e32 v114, v114
	s_waitcnt lgkmcnt(7)
	v_mfma_f32_16x16x32_bf16 v[66:69], v[222:225], v[126:129], v[66:69]
	v_exp_f32_e32 v115, v115
	s_waitcnt lgkmcnt(6)
	v_mfma_f32_16x16x32_bf16 v[62:65], v[226:229], v[126:129], v[62:65]
	v_exp_f32_e32 v116, v116
	s_waitcnt lgkmcnt(5)
	v_mfma_f32_16x16x32_bf16 v[58:61], v[230:233], v[126:129], v[58:61]
	v_exp_f32_e32 v117, v117
	s_waitcnt lgkmcnt(4)
	v_mfma_f32_16x16x32_bf16 v[54:57], v[234:237], v[126:129], v[54:57]
	v_exp_f32_e32 v118, v118
	s_waitcnt lgkmcnt(3)
	v_mfma_f32_16x16x32_bf16 v[50:53], v[238:241], v[126:129], v[50:53]
	v_exp_f32_e32 v119, v119
	v_cvt_pk_bf16_f32 v114, v114, v115
	s_waitcnt lgkmcnt(2)
	v_mfma_f32_16x16x32_bf16 v[46:49], v[242:245], v[126:129], v[46:49]
	v_exp_f32_e32 v120, v120
	v_cvt_pk_bf16_f32 v115, v116, v117
	s_waitcnt lgkmcnt(1)
	v_mfma_f32_16x16x32_bf16 v[42:45], v[246:249], v[126:129], v[42:45]
	v_exp_f32_e32 v121, v121
	v_cvt_pk_bf16_f32 v116, v118, v119
	s_waitcnt lgkmcnt(0)
	v_mfma_f32_16x16x32_bf16 v[34:37], v[250:253], v[126:129], v[34:37]
	v_cvt_pk_bf16_f32 v117, v120, v121
	s_nop 1
	v_mfma_f32_16x16x32_bf16 v[38:41], v[206:209], v[114:117], v[38:41]
	v_exp_f32_e32 v138, v138
	v_mfma_f32_16x16x32_bf16 v[30:33], v[222:225], v[114:117], v[30:33]
	ds_read_b128 v[222:225], v178 offset:9280
	v_exp_f32_e32 v139, v139
	v_mfma_f32_16x16x32_bf16 v[26:29], v[226:229], v[114:117], v[26:29]
	ds_read_b128 v[226:229], v210 offset:11520
	v_exp_f32_e32 v140, v140
	v_mfma_f32_16x16x32_bf16 v[22:25], v[230:233], v[114:117], v[22:25]
	ds_read_b128 v[230:233], v211 offset:13824
	v_exp_f32_e32 v141, v141
	v_mfma_f32_16x16x32_bf16 v[10:13], v[234:237], v[114:117], v[10:13]
	ds_read_b128 v[234:237], v212 offset:16128
	v_exp_f32_e32 v142, v142
	v_mfma_f32_16x16x32_bf16 v[18:21], v[238:241], v[114:117], v[18:21]
	ds_read_b128 v[238:241], v178 offset:18432
	v_exp_f32_e32 v143, v143
	v_cvt_pk_bf16_f32 v130, v138, v139
	v_mfma_f32_16x16x32_bf16 v[14:17], v[242:245], v[114:117], v[14:17]
	ds_read_b128 v[242:245], v178 offset:20752
	v_exp_f32_e32 v144, v144
	v_cvt_pk_bf16_f32 v131, v140, v141
	v_mfma_f32_16x16x32_bf16 v[6:9], v[246:249], v[114:117], v[6:9]
	ds_read_b128 v[246:249], v178 offset:23072
	v_exp_f32_e32 v145, v145
	v_cvt_pk_bf16_f32 v132, v142, v143
	v_mfma_f32_16x16x32_bf16 v[2:5], v[250:253], v[114:117], v[2:5]
	ds_read_b128 v[250:253], v178 offset:25392
	v_cvt_pk_bf16_f32 v133, v144, v145
	s_nop 1
	v_mfma_f32_16x16x32_bf16 v[70:73], v[206:209], v[130:133], v[70:73]
	v_exp_f32_e32 v122, v122
	s_waitcnt lgkmcnt(7)
	v_mfma_f32_16x16x32_bf16 v[66:69], v[222:225], v[130:133], v[66:69]
	v_exp_f32_e32 v123, v123
	s_waitcnt lgkmcnt(6)
	v_mfma_f32_16x16x32_bf16 v[62:65], v[226:229], v[130:133], v[62:65]
	v_exp_f32_e32 v124, v124
	s_waitcnt lgkmcnt(5)
	v_mfma_f32_16x16x32_bf16 v[58:61], v[230:233], v[130:133], v[58:61]
	v_exp_f32_e32 v125, v125
	s_waitcnt lgkmcnt(4)
	v_mfma_f32_16x16x32_bf16 v[54:57], v[234:237], v[130:133], v[54:57]
	v_exp_f32_e32 v134, v134
	s_waitcnt lgkmcnt(3)
	v_mfma_f32_16x16x32_bf16 v[50:53], v[238:241], v[130:133], v[50:53]
	v_exp_f32_e32 v135, v135
	v_cvt_pk_bf16_f32 v118, v122, v123
	s_waitcnt lgkmcnt(2)
	v_mfma_f32_16x16x32_bf16 v[46:49], v[242:245], v[130:133], v[46:49]
	v_exp_f32_e32 v136, v136
	v_cvt_pk_bf16_f32 v119, v124, v125
	s_waitcnt lgkmcnt(1)
	v_mfma_f32_16x16x32_bf16 v[42:45], v[246:249], v[130:133], v[42:45]
	v_exp_f32_e32 v137, v137
	v_cvt_pk_bf16_f32 v120, v134, v135
	s_waitcnt lgkmcnt(0)
	v_mfma_f32_16x16x32_bf16 v[34:37], v[250:253], v[130:133], v[34:37]
	v_cvt_pk_bf16_f32 v121, v136, v137
	s_nop 1
	v_mfma_f32_16x16x32_bf16 v[38:41], v[206:209], v[118:121], v[38:41]
	s_bitcmp1_b32 s68, 0
	s_cselect_b32 s21, 0x6c00, 0
	s_add_i32 s22, s21, 0
	v_mfma_f32_16x16x32_bf16 v[30:33], v[222:225], v[118:121], v[30:33]
	v_add3_u32 v213, s22, v171, v0
	ds_write_b128 v213, v[110:113]
	v_mfma_f32_16x16x32_bf16 v[26:29], v[226:229], v[118:121], v[26:29]
	v_and_b32_e32 v110, 0xffff, v102
	v_add3_u32 v111, s22, v170, v172
	v_lshrrev_b32_e32 v102, 16, v102
	v_mfma_f32_16x16x32_bf16 v[22:25], v[230:233], v[118:121], v[22:25]
	v_lshl_or_b32 v110, v106, 16, v110
	v_and_or_b32 v102, v106, s33, v102
	v_add_u32_e32 v106, 0x2400, v111
	v_mfma_f32_16x16x32_bf16 v[10:13], v[234:237], v[118:121], v[10:13]
	ds_write2_b32 v106, v110, v102 offset1:36
	v_and_b32_e32 v102, 0xffff, v103
	v_lshrrev_b32_e32 v103, 16, v103
	v_mfma_f32_16x16x32_bf16 v[18:21], v[238:241], v[118:121], v[18:21]
	v_lshl_or_b32 v102, v107, 16, v102
	v_and_or_b32 v103, v107, s33, v103
	ds_write2_b32 v106, v102, v103 offset0:72 offset1:108
	v_mfma_f32_16x16x32_bf16 v[14:17], v[242:245], v[118:121], v[14:17]
	v_and_b32_e32 v102, 0xffff, v104
	v_lshrrev_b32_e32 v103, 16, v104
	v_lshl_or_b32 v102, v108, 16, v102
	v_mfma_f32_16x16x32_bf16 v[6:9], v[246:249], v[118:121], v[6:9]
	v_and_or_b32 v103, v108, s33, v103
	ds_write2_b32 v106, v102, v103 offset0:144 offset1:180
	v_and_b32_e32 v102, 0xffff, v105
	v_mfma_f32_16x16x32_bf16 v[2:5], v[250:253], v[118:121], v[2:5]
	v_lshrrev_b32_e32 v103, 16, v105
	v_lshl_or_b32 v102, v109, 16, v102
	v_and_or_b32 v103, v109, s33, v103
	ds_write2_b32 v106, v102, v103 offset0:216 offset1:252
	s_branch .Lattn_stage_b

; __device__ __forceinline__ void unit(unsigned char* ws, LAS unsigned char* lds, int b, int h, int mp, int qb, const int tid_in) {
;     ...
;         if (kt + 1 < NT) { FA3_STAGE((kt + 1) & 1); kA = kB; vA0 = vB0; vA1 = vB1;
;             if (kt + 3 < NT) { const size_t off = (size_t)(kt + 3) * 64 * 512; kB = *(const u32x4*)(kg + off); vB0 = *(const u32x4*)(vg + off); vB1 = *(const u32x4*)(vg + off + 512); } }
.Lattn_stage_b:
	s_waitcnt vmcnt(0)
	v_mov_b64_e32 v[110:111], v[90:91]
	v_mov_b64_e32 v[112:113], v[92:93]
	v_mov_b64_e32 v[102:103], v[94:95]
	v_mov_b64_e32 v[104:105], v[96:97]
	v_mov_b64_e32 v[106:107], v[98:99]
	v_mov_b64_e32 v[108:109], v[100:101]
	s_cmp_ge_u32 s68, s70
	s_cbranch_scc1 .LBB0_198
	v_lshl_add_u64 v[114:115], v[160:161], 0, s[14:15]
	v_add_co_u32_e32 v114, vcc, 0xa630000, v114
	v_lshl_add_u64 v[116:117], v[162:163], 0, s[14:15]
	s_nop 0
	v_addc_co_u32_e32 v115, vcc, 0, v115, vcc
	global_load_dwordx4 v[90:93], v[116:117], off
	global_load_dwordx4 v[94:97], v[114:115], off
	global_load_dwordx4 v[98:101], v[114:115], off offset:1024
